# indexer key-tile loop: heads software-pipelined over 3 accumulators, no canonicalize max (on top of attention loop change)
# speedup vs baseline: 1.0270x; 1.0152x over previous
.LBB0_639:
	s_waitcnt vmcnt(2)
	v_mov_b64_e32 v[134:135], v[78:79]
	v_mov_b64_e32 v[132:133], v[76:77]
	v_mov_b64_e32 v[130:131], v[74:75]
	v_mov_b64_e32 v[128:129], v[72:73]
	s_add_i32 s0, s9, 1
	v_min_i32_e32 v72, s0, v139
	s_add_i32 s0, s9, 2
	v_min_i32_e32 v88, s0, v139
	s_add_i32 s0, s9, 3
	s_add_i32 s8, s9, 4
	v_min_i32_e32 v96, s0, v139
	v_min_i32_e32 v104, s8, v139
	v_lshl_add_u32 v72, v72, 6, v138
	v_lshl_add_u32 v88, v88, 6, v138
	v_lshl_add_u32 v96, v96, 6, v138
	v_lshl_add_u32 v104, v104, 6, v138
	v_ashrrev_i32_e32 v73, 31, v72
	v_ashrrev_i32_e32 v89, 31, v88
	v_ashrrev_i32_e32 v97, 31, v96
	v_ashrrev_i32_e32 v105, 31, v104
	v_lshlrev_b64 v[72:73], 7, v[72:73]
	v_lshlrev_b64 v[88:89], 7, v[88:89]
	v_lshlrev_b64 v[96:97], 7, v[96:97]
	v_lshlrev_b64 v[104:105], 7, v[104:105]
	v_lshl_add_u64 v[72:73], v[140:141], 0, v[72:73]
	v_lshl_add_u64 v[92:93], v[140:141], 0, v[88:89]
	v_lshl_add_u64 v[100:101], v[140:141], 0, v[96:97]
	v_lshl_add_u64 v[108:109], v[140:141], 0, v[104:105]
	global_load_dwordx4 v[76:79], v[72:73], off
	s_nop 0
	global_load_dwordx4 v[72:75], v[72:73], off offset:64
	s_nop 0
	global_load_dwordx4 v[88:91], v[92:93], off
	s_nop 0
	global_load_dwordx4 v[92:95], v[92:93], off offset:64
	s_nop 0
	global_load_dwordx4 v[96:99], v[100:101], off
	s_nop 0
	global_load_dwordx4 v[100:103], v[100:101], off offset:64
	s_nop 0
	global_load_dwordx4 v[104:107], v[108:109], off
	s_nop 0
	global_load_dwordx4 v[108:111], v[108:109], off offset:64
	v_mfma_f32_16x16x32_bf16 v[200:203], v[132:135], v[68:71], 0
	v_mfma_f32_16x16x32_bf16 v[200:203], v[128:131], v[64:67], v[200:203]
	v_mfma_f32_16x16x32_bf16 v[204:207], v[132:135], v[60:63], 0
	v_mfma_f32_16x16x32_bf16 v[204:207], v[128:131], v[56:59], v[204:207]
	v_mfma_f32_16x16x32_bf16 v[208:211], v[132:135], v[52:55], 0
	v_mfma_f32_16x16x32_bf16 v[208:211], v[128:131], v[48:51], v[208:211]
	s_nop 3
	v_max_f32_e32 v212, 0, v200
	v_max_f32_e32 v213, 0, v201
	v_max_f32_e32 v214, 0, v202
	v_max_f32_e32 v215, 0, v203
	v_pk_fma_f32 v[216:217], v[0:1], v[212:213], 0 op_sel_hi:[1,1,0]
	v_pk_fma_f32 v[218:219], v[0:1], v[214:215], 0 op_sel_hi:[1,1,0]
	v_mfma_f32_16x16x32_bf16 v[200:203], v[132:135], v[44:47], 0
	v_mfma_f32_16x16x32_bf16 v[200:203], v[128:131], v[40:43], v[200:203]
	v_max_f32_e32 v212, 0, v204
	v_max_f32_e32 v213, 0, v205
	v_max_f32_e32 v214, 0, v206
	v_max_f32_e32 v215, 0, v207
	v_pk_fma_f32 v[216:217], v[148:149], v[212:213], v[216:217]
	v_pk_fma_f32 v[218:219], v[148:149], v[214:215], v[218:219]
	v_mfma_f32_16x16x32_bf16 v[204:207], v[132:135], v[36:39], 0
	v_mfma_f32_16x16x32_bf16 v[204:207], v[128:131], v[32:35], v[204:207]
	v_max_f32_e32 v212, 0, v208
	v_max_f32_e32 v213, 0, v209
	v_max_f32_e32 v214, 0, v210
	v_max_f32_e32 v215, 0, v211
	v_pk_fma_f32 v[216:217], v[142:143], v[212:213], v[216:217]
	v_pk_fma_f32 v[218:219], v[142:143], v[214:215], v[218:219]
	v_mfma_f32_16x16x32_bf16 v[208:211], v[132:135], v[28:31], 0
	v_mfma_f32_16x16x32_bf16 v[208:211], v[128:131], v[24:27], v[208:211]
	v_max_f32_e32 v212, 0, v200
	v_max_f32_e32 v213, 0, v201
	v_max_f32_e32 v214, 0, v202
	v_max_f32_e32 v215, 0, v203
	v_pk_fma_f32 v[216:217], v[2:3], v[212:213], v[216:217]
	v_pk_fma_f32 v[218:219], v[2:3], v[214:215], v[218:219]
	v_mfma_f32_16x16x32_bf16 v[200:203], v[132:135], v[20:23], 0
	v_mfma_f32_16x16x32_bf16 v[200:203], v[128:131], v[16:19], v[200:203]
	v_max_f32_e32 v212, 0, v204
	v_max_f32_e32 v213, 0, v205
	v_max_f32_e32 v214, 0, v206
	v_max_f32_e32 v215, 0, v207
	v_pk_fma_f32 v[216:217], v[144:145], v[212:213], v[216:217]
	v_pk_fma_f32 v[218:219], v[144:145], v[214:215], v[218:219]
	v_mfma_f32_16x16x32_bf16 v[204:207], v[132:135], v[12:15], 0
	v_mfma_f32_16x16x32_bf16 v[204:207], v[128:131], v[8:11], v[204:207]
	v_max_f32_e32 v212, 0, v208
	v_max_f32_e32 v213, 0, v209
	v_max_f32_e32 v214, 0, v210
	v_max_f32_e32 v215, 0, v211
	v_pk_fma_f32 v[216:217], v[4:5], v[212:213], v[216:217]
	v_pk_fma_f32 v[218:219], v[4:5], v[214:215], v[218:219]
	v_max_f32_e32 v212, 0, v200
	v_max_f32_e32 v213, 0, v201
	v_max_f32_e32 v214, 0, v202
	v_max_f32_e32 v215, 0, v203
	v_pk_fma_f32 v[216:217], v[146:147], v[212:213], v[216:217]
	v_pk_fma_f32 v[218:219], v[146:147], v[214:215], v[218:219]
	v_max_f32_e32 v212, 0, v204
	v_max_f32_e32 v213, 0, v205
	v_max_f32_e32 v214, 0, v206
	v_max_f32_e32 v215, 0, v207
	v_pk_fma_f32 v[216:217], v[6:7], v[212:213], v[216:217]
	v_pk_fma_f32 v[218:219], v[6:7], v[214:215], v[218:219]
	v_cvt_pk_f16_f32 v220, v216, v217
	v_xor_b32_e32 v221, -1, v220
	v_xor_b32_e32 v222, 0x80008000, v220
	v_cmp_gt_i16_e64 s[0:1], 0, v220
	v_cmp_lt_i16_sdwa vcc, v220, v137 src0_sel:WORD_1 src1_sel:DWORD
	v_lshrrev_b32_e32 v223, 16, v221
	v_cndmask_b32_e64 v224, v222, v221, s[0:1]
	v_lshrrev_b32_e32 v225, 16, v222
	v_cndmask_b32_e32 v226, v225, v223, vcc
	v_cvt_pk_f16_f32 v220, v218, v219
	v_xor_b32_e32 v221, -1, v220
	v_xor_b32_e32 v222, 0x80008000, v220
	v_cmp_lt_i16_sdwa vcc, v220, v137 src0_sel:WORD_1 src1_sel:DWORD
	v_cmp_gt_i16_e64 s[0:1], 0, v220
	s_nop 1
	v_cndmask_b32_e64 v223, v222, v221, s[0:1]
	v_cndmask_b32_sdwa v225, v222, v221, vcc dst_sel:DWORD dst_unused:UNUSED_PAD src0_sel:WORD_1 src1_sel:WORD_1
	v_perm_b32 v229, v225, v223, s10
	v_perm_b32 v228, v226, v224, s10
	ds_write_b64 v158, v[228:229]
	s_add_i32 s0, s9, -2
	v_cmp_lt_i32_e32 vcc, s0, v156
	s_and_saveexec_b64 s[6:7], vcc
	s_cbranch_execz .LBB0_641
	s_waitcnt vmcnt(8)
	v_mfma_f32_16x16x32_bf16 v[200:203], v[124:127], v[68:71], 0
	v_mfma_f32_16x16x32_bf16 v[200:203], v[120:123], v[64:67], v[200:203]
	v_mfma_f32_16x16x32_bf16 v[204:207], v[124:127], v[60:63], 0
	v_mfma_f32_16x16x32_bf16 v[204:207], v[120:123], v[56:59], v[204:207]
	v_mfma_f32_16x16x32_bf16 v[208:211], v[124:127], v[52:55], 0
	v_mfma_f32_16x16x32_bf16 v[208:211], v[120:123], v[48:51], v[208:211]
	s_nop 3
	v_max_f32_e32 v212, 0, v200
	v_max_f32_e32 v213, 0, v201
	v_max_f32_e32 v214, 0, v202
	v_max_f32_e32 v215, 0, v203
	v_pk_fma_f32 v[216:217], v[0:1], v[212:213], 0 op_sel_hi:[1,1,0]
	v_pk_fma_f32 v[218:219], v[0:1], v[214:215], 0 op_sel_hi:[1,1,0]
	v_mfma_f32_16x16x32_bf16 v[200:203], v[124:127], v[44:47], 0
	v_mfma_f32_16x16x32_bf16 v[200:203], v[120:123], v[40:43], v[200:203]
	v_max_f32_e32 v212, 0, v204
	v_max_f32_e32 v213, 0, v205
	v_max_f32_e32 v214, 0, v206
	v_max_f32_e32 v215, 0, v207
	v_pk_fma_f32 v[216:217], v[148:149], v[212:213], v[216:217]
	v_pk_fma_f32 v[218:219], v[148:149], v[214:215], v[218:219]
	v_mfma_f32_16x16x32_bf16 v[204:207], v[124:127], v[36:39], 0
	v_mfma_f32_16x16x32_bf16 v[204:207], v[120:123], v[32:35], v[204:207]
	v_max_f32_e32 v212, 0, v208
	v_max_f32_e32 v213, 0, v209
	v_max_f32_e32 v214, 0, v210
	v_max_f32_e32 v215, 0, v211
	v_pk_fma_f32 v[216:217], v[142:143], v[212:213], v[216:217]
	v_pk_fma_f32 v[218:219], v[142:143], v[214:215], v[218:219]
	v_mfma_f32_16x16x32_bf16 v[208:211], v[124:127], v[28:31], 0
	v_mfma_f32_16x16x32_bf16 v[208:211], v[120:123], v[24:27], v[208:211]
	v_max_f32_e32 v212, 0, v200
	v_max_f32_e32 v213, 0, v201
	v_max_f32_e32 v214, 0, v202
	v_max_f32_e32 v215, 0, v203
	v_pk_fma_f32 v[216:217], v[2:3], v[212:213], v[216:217]
	v_pk_fma_f32 v[218:219], v[2:3], v[214:215], v[218:219]
	v_mfma_f32_16x16x32_bf16 v[200:203], v[124:127], v[20:23], 0
	v_mfma_f32_16x16x32_bf16 v[200:203], v[120:123], v[16:19], v[200:203]
	v_max_f32_e32 v212, 0, v204
	v_max_f32_e32 v213, 0, v205
	v_max_f32_e32 v214, 0, v206
	v_max_f32_e32 v215, 0, v207
	v_pk_fma_f32 v[216:217], v[144:145], v[212:213], v[216:217]
	v_pk_fma_f32 v[218:219], v[144:145], v[214:215], v[218:219]
	v_mfma_f32_16x16x32_bf16 v[204:207], v[124:127], v[12:15], 0
	v_mfma_f32_16x16x32_bf16 v[204:207], v[120:123], v[8:11], v[204:207]
	v_max_f32_e32 v212, 0, v208
	v_max_f32_e32 v213, 0, v209
	v_max_f32_e32 v214, 0, v210
	v_max_f32_e32 v215, 0, v211
	v_pk_fma_f32 v[216:217], v[4:5], v[212:213], v[216:217]
	v_pk_fma_f32 v[218:219], v[4:5], v[214:215], v[218:219]
	v_max_f32_e32 v212, 0, v200
	v_max_f32_e32 v213, 0, v201
	v_max_f32_e32 v214, 0, v202
	v_max_f32_e32 v215, 0, v203
	v_pk_fma_f32 v[216:217], v[146:147], v[212:213], v[216:217]
	v_pk_fma_f32 v[218:219], v[146:147], v[214:215], v[218:219]
	v_max_f32_e32 v212, 0, v204
	v_max_f32_e32 v213, 0, v205
	v_max_f32_e32 v214, 0, v206
	v_max_f32_e32 v215, 0, v207
	v_pk_fma_f32 v[216:217], v[6:7], v[212:213], v[216:217]
	v_pk_fma_f32 v[218:219], v[6:7], v[214:215], v[218:219]
	v_cvt_pk_f16_f32 v220, v216, v217
	v_xor_b32_e32 v221, -1, v220
	v_xor_b32_e32 v222, 0x80008000, v220
	v_cmp_gt_i16_e64 s[0:1], 0, v220
	v_cmp_lt_i16_sdwa vcc, v220, v137 src0_sel:WORD_1 src1_sel:DWORD
	v_lshrrev_b32_e32 v223, 16, v221
	v_cndmask_b32_e64 v224, v222, v221, s[0:1]
	v_lshrrev_b32_e32 v225, 16, v222
	v_cndmask_b32_e32 v226, v225, v223, vcc
	v_cvt_pk_f16_f32 v220, v218, v219
	v_xor_b32_e32 v221, -1, v220
	v_xor_b32_e32 v222, 0x80008000, v220
	v_cmp_lt_i16_sdwa vcc, v220, v137 src0_sel:WORD_1 src1_sel:DWORD
	v_cmp_gt_i16_e64 s[0:1], 0, v220
	s_nop 1
	v_cndmask_b32_e64 v223, v222, v221, s[0:1]
	v_cndmask_b32_sdwa v225, v222, v221, vcc dst_sel:DWORD dst_unused:UNUSED_PAD src0_sel:WORD_1 src1_sel:WORD_1
	v_perm_b32 v229, v225, v223, s10
	v_perm_b32 v228, v226, v224, s10
	ds_write_b64 v158, v[228:229] offset:128
.LBB0_641:
	s_or_b64 exec, exec, s[6:7]
	s_add_i32 s0, s9, -1
	v_cmp_lt_i32_e32 vcc, s0, v156
	s_and_saveexec_b64 s[6:7], vcc
	s_cbranch_execz .LBB0_643
	s_waitcnt vmcnt(8)
	v_mfma_f32_16x16x32_bf16 v[200:203], v[116:119], v[68:71], 0
	v_mfma_f32_16x16x32_bf16 v[200:203], v[112:115], v[64:67], v[200:203]
	v_mfma_f32_16x16x32_bf16 v[204:207], v[116:119], v[60:63], 0
	v_mfma_f32_16x16x32_bf16 v[204:207], v[112:115], v[56:59], v[204:207]
	v_mfma_f32_16x16x32_bf16 v[208:211], v[116:119], v[52:55], 0
	v_mfma_f32_16x16x32_bf16 v[208:211], v[112:115], v[48:51], v[208:211]
	s_nop 3
	v_max_f32_e32 v212, 0, v200
	v_max_f32_e32 v213, 0, v201
	v_max_f32_e32 v214, 0, v202
	v_max_f32_e32 v215, 0, v203
	v_pk_fma_f32 v[216:217], v[0:1], v[212:213], 0 op_sel_hi:[1,1,0]
	v_pk_fma_f32 v[218:219], v[0:1], v[214:215], 0 op_sel_hi:[1,1,0]
	v_mfma_f32_16x16x32_bf16 v[200:203], v[116:119], v[44:47], 0
	v_mfma_f32_16x16x32_bf16 v[200:203], v[112:115], v[40:43], v[200:203]
	v_max_f32_e32 v212, 0, v204
	v_max_f32_e32 v213, 0, v205
	v_max_f32_e32 v214, 0, v206
	v_max_f32_e32 v215, 0, v207
	v_pk_fma_f32 v[216:217], v[148:149], v[212:213], v[216:217]
	v_pk_fma_f32 v[218:219], v[148:149], v[214:215], v[218:219]
	v_mfma_f32_16x16x32_bf16 v[204:207], v[116:119], v[36:39], 0
	v_mfma_f32_16x16x32_bf16 v[204:207], v[112:115], v[32:35], v[204:207]
	v_max_f32_e32 v212, 0, v208
	v_max_f32_e32 v213, 0, v209
	v_max_f32_e32 v214, 0, v210
	v_max_f32_e32 v215, 0, v211
	v_pk_fma_f32 v[216:217], v[142:143], v[212:213], v[216:217]
	v_pk_fma_f32 v[218:219], v[142:143], v[214:215], v[218:219]
	v_mfma_f32_16x16x32_bf16 v[208:211], v[116:119], v[28:31], 0
	v_mfma_f32_16x16x32_bf16 v[208:211], v[112:115], v[24:27], v[208:211]
	v_max_f32_e32 v212, 0, v200
	v_max_f32_e32 v213, 0, v201
	v_max_f32_e32 v214, 0, v202
	v_max_f32_e32 v215, 0, v203
	v_pk_fma_f32 v[216:217], v[2:3], v[212:213], v[216:217]
	v_pk_fma_f32 v[218:219], v[2:3], v[214:215], v[218:219]
	v_mfma_f32_16x16x32_bf16 v[200:203], v[116:119], v[20:23], 0
	v_mfma_f32_16x16x32_bf16 v[200:203], v[112:115], v[16:19], v[200:203]
	v_max_f32_e32 v212, 0, v204
	v_max_f32_e32 v213, 0, v205
	v_max_f32_e32 v214, 0, v206
	v_max_f32_e32 v215, 0, v207
	v_pk_fma_f32 v[216:217], v[144:145], v[212:213], v[216:217]
	v_pk_fma_f32 v[218:219], v[144:145], v[214:215], v[218:219]
	v_mfma_f32_16x16x32_bf16 v[204:207], v[116:119], v[12:15], 0
	v_mfma_f32_16x16x32_bf16 v[204:207], v[112:115], v[8:11], v[204:207]
	v_max_f32_e32 v212, 0, v208
	v_max_f32_e32 v213, 0, v209
	v_max_f32_e32 v214, 0, v210
	v_max_f32_e32 v215, 0, v211
	v_pk_fma_f32 v[216:217], v[4:5], v[212:213], v[216:217]
	v_pk_fma_f32 v[218:219], v[4:5], v[214:215], v[218:219]
	v_max_f32_e32 v212, 0, v200
	v_max_f32_e32 v213, 0, v201
	v_max_f32_e32 v214, 0, v202
	v_max_f32_e32 v215, 0, v203
	v_pk_fma_f32 v[216:217], v[146:147], v[212:213], v[216:217]
	v_pk_fma_f32 v[218:219], v[146:147], v[214:215], v[218:219]
	v_max_f32_e32 v212, 0, v204
	v_max_f32_e32 v213, 0, v205
	v_max_f32_e32 v214, 0, v206
	v_max_f32_e32 v215, 0, v207
	v_pk_fma_f32 v[216:217], v[6:7], v[212:213], v[216:217]
	v_pk_fma_f32 v[218:219], v[6:7], v[214:215], v[218:219]
	v_cvt_pk_f16_f32 v220, v216, v217
	v_xor_b32_e32 v221, -1, v220
	v_xor_b32_e32 v222, 0x80008000, v220
	v_cmp_gt_i16_e64 s[0:1], 0, v220
	v_cmp_lt_i16_sdwa vcc, v220, v137 src0_sel:WORD_1 src1_sel:DWORD
	v_lshrrev_b32_e32 v223, 16, v221
	v_cndmask_b32_e64 v224, v222, v221, s[0:1]
	v_lshrrev_b32_e32 v225, 16, v222
	v_cndmask_b32_e32 v226, v225, v223, vcc
	v_cvt_pk_f16_f32 v220, v218, v219
	v_xor_b32_e32 v221, -1, v220
	v_xor_b32_e32 v222, 0x80008000, v220
	v_cmp_lt_i16_sdwa vcc, v220, v137 src0_sel:WORD_1 src1_sel:DWORD
	v_cmp_gt_i16_e64 s[0:1], 0, v220
	s_nop 1
	v_cndmask_b32_e64 v223, v222, v221, s[0:1]
	v_cndmask_b32_sdwa v225, v222, v221, vcc dst_sel:DWORD dst_unused:UNUSED_PAD src0_sel:WORD_1 src1_sel:WORD_1
	v_perm_b32 v229, v225, v223, s10
	v_perm_b32 v228, v226, v224, s10
	ds_write_b64 v158, v[228:229] offset:256
.LBB0_643:
	s_or_b64 exec, exec, s[6:7]
	v_cmp_lt_i32_e32 vcc, s9, v156
	s_and_saveexec_b64 s[6:7], vcc
	s_cbranch_execz .LBB0_638
	s_waitcnt vmcnt(8)
	v_mfma_f32_16x16x32_bf16 v[200:203], v[84:87], v[68:71], 0
	v_mfma_f32_16x16x32_bf16 v[200:203], v[80:83], v[64:67], v[200:203]
	v_mfma_f32_16x16x32_bf16 v[204:207], v[84:87], v[60:63], 0
	v_mfma_f32_16x16x32_bf16 v[204:207], v[80:83], v[56:59], v[204:207]
	v_mfma_f32_16x16x32_bf16 v[208:211], v[84:87], v[52:55], 0
	v_mfma_f32_16x16x32_bf16 v[208:211], v[80:83], v[48:51], v[208:211]
	s_nop 3
	v_max_f32_e32 v212, 0, v200
	v_max_f32_e32 v213, 0, v201
	v_max_f32_e32 v214, 0, v202
	v_max_f32_e32 v215, 0, v203
	v_pk_fma_f32 v[216:217], v[0:1], v[212:213], 0 op_sel_hi:[1,1,0]
	v_pk_fma_f32 v[218:219], v[0:1], v[214:215], 0 op_sel_hi:[1,1,0]
	v_mfma_f32_16x16x32_bf16 v[200:203], v[84:87], v[44:47], 0
	v_mfma_f32_16x16x32_bf16 v[200:203], v[80:83], v[40:43], v[200:203]
	v_max_f32_e32 v212, 0, v204
	v_max_f32_e32 v213, 0, v205
	v_max_f32_e32 v214, 0, v206
	v_max_f32_e32 v215, 0, v207
	v_pk_fma_f32 v[216:217], v[148:149], v[212:213], v[216:217]
	v_pk_fma_f32 v[218:219], v[148:149], v[214:215], v[218:219]
	v_mfma_f32_16x16x32_bf16 v[204:207], v[84:87], v[36:39], 0
	v_mfma_f32_16x16x32_bf16 v[204:207], v[80:83], v[32:35], v[204:207]
	v_max_f32_e32 v212, 0, v208
	v_max_f32_e32 v213, 0, v209
	v_max_f32_e32 v214, 0, v210
	v_max_f32_e32 v215, 0, v211
	v_pk_fma_f32 v[216:217], v[142:143], v[212:213], v[216:217]
	v_pk_fma_f32 v[218:219], v[142:143], v[214:215], v[218:219]
	v_mfma_f32_16x16x32_bf16 v[208:211], v[84:87], v[28:31], 0
	v_mfma_f32_16x16x32_bf16 v[208:211], v[80:83], v[24:27], v[208:211]
	v_max_f32_e32 v212, 0, v200
	v_max_f32_e32 v213, 0, v201
	v_max_f32_e32 v214, 0, v202
	v_max_f32_e32 v215, 0, v203
	v_pk_fma_f32 v[216:217], v[2:3], v[212:213], v[216:217]
	v_pk_fma_f32 v[218:219], v[2:3], v[214:215], v[218:219]
	v_mfma_f32_16x16x32_bf16 v[200:203], v[84:87], v[20:23], 0
	v_mfma_f32_16x16x32_bf16 v[200:203], v[80:83], v[16:19], v[200:203]
	v_max_f32_e32 v212, 0, v204
	v_max_f32_e32 v213, 0, v205
	v_max_f32_e32 v214, 0, v206
	v_max_f32_e32 v215, 0, v207
	v_pk_fma_f32 v[216:217], v[144:145], v[212:213], v[216:217]
	v_pk_fma_f32 v[218:219], v[144:145], v[214:215], v[218:219]
	v_mfma_f32_16x16x32_bf16 v[204:207], v[84:87], v[12:15], 0
	v_mfma_f32_16x16x32_bf16 v[204:207], v[80:83], v[8:11], v[204:207]
	v_max_f32_e32 v212, 0, v208
	v_max_f32_e32 v213, 0, v209
	v_max_f32_e32 v214, 0, v210
	v_max_f32_e32 v215, 0, v211
	v_pk_fma_f32 v[216:217], v[4:5], v[212:213], v[216:217]
	v_pk_fma_f32 v[218:219], v[4:5], v[214:215], v[218:219]
	v_max_f32_e32 v212, 0, v200
	v_max_f32_e32 v213, 0, v201
	v_max_f32_e32 v214, 0, v202
	v_max_f32_e32 v215, 0, v203
	v_pk_fma_f32 v[216:217], v[146:147], v[212:213], v[216:217]
	v_pk_fma_f32 v[218:219], v[146:147], v[214:215], v[218:219]
	v_max_f32_e32 v212, 0, v204
	v_max_f32_e32 v213, 0, v205
	v_max_f32_e32 v214, 0, v206
	v_max_f32_e32 v215, 0, v207
	v_pk_fma_f32 v[216:217], v[6:7], v[212:213], v[216:217]
	v_pk_fma_f32 v[218:219], v[6:7], v[214:215], v[218:219]
	v_cvt_pk_f16_f32 v220, v216, v217
	v_xor_b32_e32 v221, -1, v220
	v_xor_b32_e32 v222, 0x80008000, v220
	v_cmp_gt_i16_e64 s[0:1], 0, v220
	v_cmp_lt_i16_sdwa vcc, v220, v137 src0_sel:WORD_1 src1_sel:DWORD
	v_lshrrev_b32_e32 v223, 16, v221
	v_cndmask_b32_e64 v224, v222, v221, s[0:1]
	v_lshrrev_b32_e32 v225, 16, v222
	v_cndmask_b32_e32 v226, v225, v223, vcc
	v_cvt_pk_f16_f32 v220, v218, v219
	v_xor_b32_e32 v221, -1, v220
	v_xor_b32_e32 v222, 0x80008000, v220
	v_cmp_lt_i16_sdwa vcc, v220, v137 src0_sel:WORD_1 src1_sel:DWORD
	v_cmp_gt_i16_e64 s[0:1], 0, v220
	s_nop 1
	v_cndmask_b32_e64 v223, v222, v221, s[0:1]
	v_cndmask_b32_sdwa v225, v222, v221, vcc dst_sel:DWORD dst_unused:UNUSED_PAD src0_sel:WORD_1 src1_sel:WORD_1
	v_perm_b32 v229, v225, v223, s10
	v_perm_b32 v228, v226, v224, s10
	ds_write_b64 v158, v[228:229] offset:384
	s_branch .LBB0_638
